# back-to-back redundant s_barrier removed at the ends of P6, P8 and P9
# speedup vs baseline: 1.0006x; 1.0005x over previous
; #define PG8_WAIT_V(n) asm volatile("s_waitcnt vmcnt(" #n ")" ::: "memory")
; #define PG8_BAR __builtin_amdgcn_s_barrier()
; __device__ __forceinline__ unsigned xb_add(unsigned* p, unsigned v) { return __hip_atomic_fetch_add(p, v, __ATOMIC_RELAXED, __HIP_MEMORY_SCOPE_AGENT); }
; template <class Epi, class Sched, bool ALIGN_EPI>
; __device__ __forceinline__ void gemm_phase(PG8_LAS unsigned char* lds, const Gemm g, const Sched& S, const Epi& E) {
;     ...
;     PG8_WAIT_V(0);
;     if constexpr (!ALIGN_EPI) { if (wr == 0) PG8_BAR; }
;     PG8_BAR;
; __device__ __forceinline__ void team_barrier(unsigned* cnt, unsigned* tmo, unsigned& epoch, volatile LAS unsigned* same_xcd) {
;     asm volatile("s_waitcnt vmcnt(0)" ::: "memory");
;     __syncthreads();
;     if (threadIdx.x == 0) {
;         if (*same_xcd != 1u) { __builtin_amdgcn_fence(__ATOMIC_RELEASE, "agent"); }
;         asm volatile("s_waitcnt vmcnt(0)" ::: "memory");
;         (void)xb_add(cnt, 1u);
.LBB0_847:
	s_waitcnt vmcnt(0)
.LBB0_848:
	s_waitcnt vmcnt(0)
	s_waitcnt vmcnt(0)
	s_barrier
	s_and_saveexec_b64 s[0:1], s[72:73]
	s_cbranch_execz .LBB0_867
	s_add_i32 s2, 0, 0x20170
	v_mov_b32_e32 v2, s2
	ds_read_b32 v2, v2
	s_waitcnt lgkmcnt(0)
	v_cmp_eq_u32_e32 vcc, 1, v2
	s_cbranch_vccnz .LBB0_851
	buffer_wbl2 sc1

; #define PG8_WAIT_V(n) asm volatile("s_waitcnt vmcnt(" #n ")" ::: "memory")
; #define PG8_BAR __builtin_amdgcn_s_barrier()
; __device__ __forceinline__ unsigned xb_add(unsigned* p, unsigned v) { return __hip_atomic_fetch_add(p, v, __ATOMIC_RELAXED, __HIP_MEMORY_SCOPE_AGENT); }
; template <class Epi, class Sched, bool ALIGN_EPI>
; __device__ __forceinline__ void gemm_phase(PG8_LAS unsigned char* lds, const Gemm g, const Sched& S, const Epi& E) {
;     ...
;     PG8_WAIT_V(0);
;     if constexpr (!ALIGN_EPI) { if (wr == 0) PG8_BAR; }
;     PG8_BAR;
; __device__ __forceinline__ void team_barrier(unsigned* cnt, unsigned* tmo, unsigned& epoch, volatile LAS unsigned* same_xcd) {
;     asm volatile("s_waitcnt vmcnt(0)" ::: "memory");
;     __syncthreads();
;     if (threadIdx.x == 0) {
;         if (*same_xcd != 1u) { __builtin_amdgcn_fence(__ATOMIC_RELEASE, "agent"); }
;         asm volatile("s_waitcnt vmcnt(0)" ::: "memory");
;         (void)xb_add(cnt, 1u);
.LBB0_907:
	s_setprio 0
	s_waitcnt lgkmcnt(0)
	s_waitcnt vmcnt(0)
.LBB0_908:
	s_waitcnt vmcnt(0)
	s_waitcnt vmcnt(0)
	s_barrier
	s_and_saveexec_b64 s[0:1], s[72:73]
	s_cbranch_execz .LBB0_927
	s_add_i32 s2, 0, 0x20170
	v_mov_b32_e32 v1, s2
	ds_read_b32 v1, v1
	s_waitcnt lgkmcnt(0)
	v_cmp_eq_u32_e32 vcc, 1, v1
	s_cbranch_vccnz .LBB0_911
	buffer_wbl2 sc1

; #define PG8_WAIT_V(n) asm volatile("s_waitcnt vmcnt(" #n ")" ::: "memory")
; #define PG8_BAR __builtin_amdgcn_s_barrier()
; __device__ __forceinline__ unsigned xb_add(unsigned* p, unsigned v) { return __hip_atomic_fetch_add(p, v, __ATOMIC_RELAXED, __HIP_MEMORY_SCOPE_AGENT); }
; template <class Epi, class Sched, bool ALIGN_EPI>
; __device__ __forceinline__ void gemm_phase(PG8_LAS unsigned char* lds, const Gemm g, const Sched& S, const Epi& E) {
;     ...
;     PG8_WAIT_V(0);
;     if constexpr (!ALIGN_EPI) { if (wr == 0) PG8_BAR; }
;     PG8_BAR;
; __device__ __forceinline__ void team_barrier(unsigned* cnt, unsigned* tmo, unsigned& epoch, volatile LAS unsigned* same_xcd) {
;     asm volatile("s_waitcnt vmcnt(0)" ::: "memory");
;     __syncthreads();
;     if (threadIdx.x == 0) {
;         if (*same_xcd != 1u) { __builtin_amdgcn_fence(__ATOMIC_RELEASE, "agent"); }
;         asm volatile("s_waitcnt vmcnt(0)" ::: "memory");
;         (void)xb_add(cnt, 1u);
.LBB0_954:
	s_setprio 0
	s_waitcnt lgkmcnt(0)
	s_waitcnt vmcnt(0)
.LBB0_955:
	s_waitcnt vmcnt(0)
	s_waitcnt vmcnt(0)
	s_barrier
	s_and_saveexec_b64 s[0:1], s[72:73]
	s_cbranch_execz .LBB0_974
	s_add_i32 s2, 0, 0x20170
	v_mov_b32_e32 v1, s2
	ds_read_b32 v1, v1
	s_waitcnt lgkmcnt(0)
	v_cmp_eq_u32_e32 vcc, 1, v1
	s_cbranch_vccnz .LBB0_958
	buffer_wbl2 sc1
